# gate-up GEMM: row sums of squares fetched in the peeled first K iteration (no exposed load at the epilogue), SwiGLU epilogue re-derived as (g*u)*rcp((ms+eps)(1+exp2(-log2e*rs*g))) and emitted 8 wide
# speedup vs baseline: 1.0350x; 1.0119x over previous
; #define PG8_STAGE(bufoff, gbase, voff) do { _Pragma("unroll") for (int _i = 0; _i < 2; ++_i) \
;         __builtin_amdgcn_global_load_lds((const unsigned*)((const char*)(gbase) + (voff)[_i]), (PG8_LAS unsigned*)(lds + (bufoff) + ldsw + _i * 8192), 16, 0, 0); } while (0)
; #define PG8_LDA(dst, b, h) do { _Pragma("unroll") for (int m = 0; m < 4; ++m) _Pragma("unroll") for (int k = 0; k < 2; ++k) dst[m][k] = *(const PG8_LAS bf16x8*)(lds + PG8_SA(b, h) + aoff + m * 2048 + k * 1024); } while (0)
; #define PG8_LDB(dst, b, h) do { _Pragma("unroll") for (int n = 0; n < 2; ++n) _Pragma("unroll") for (int k = 0; k < 2; ++k) dst[n][k] = *(const PG8_LAS bf16x8*)(lds + PG8_SB(b, h) + boff + n * 2048 + k * 1024); } while (0)
; #define PG8_MMA(ai, bj, At, Bt) do { __builtin_amdgcn_s_setprio(1); _Pragma("unroll") for (int m = 0; m < 4; ++m) _Pragma("unroll") for (int n = 0; n < 2; ++n) _Pragma("unroll") for (int k = 0; k < 2; ++k) \
;         acc[ai][bj][m][n] = __builtin_amdgcn_mfma_f32_16x16x32_bf16(Bt[n][k], At[m][k], acc[ai][bj][m][n], 0, 0, 0); __builtin_amdgcn_s_setprio(0); } while (0)
; #define PG8_WAIT_V(n) asm volatile("s_waitcnt vmcnt(" #n ")" ::: "memory")
; #define PG8_WAIT_L(n) asm volatile("s_waitcnt lgkmcnt(" #n ")" ::: "memory")
; #define PG8_BAR __builtin_amdgcn_s_barrier()
; #define PG8_SCHED __builtin_amdgcn_sched_barrier(0)
;     __device__ __forceinline__ void operator()(const f32x4 (&acc)[2][2][4][2], const Unit& u, int wr, int wc, int fr_in, int fq_in) const {
;     ...
;         const int row0 = u.pm * BM + wr * 64 + fr, col0 = u.pn * HALF + wc * 32 + 8 * fq;
;         float ssq[2][4];
; #pragma unroll
;         for (int ai = 0; ai < 2; ++ai)
; #pragma unroll
;             for (int m = 0; m < 4; ++m) ssq[ai][m] = rowss[row0 + ai * HALF + m * 16];
;         asm volatile("" : "+v"(ssq[0][0]), "+v"(ssq[0][1]), "+v"(ssq[0][2]), "+v"(ssq[0][3]), "+v"(ssq[1][0]), "+v"(ssq[1][1]), "+v"(ssq[1][2]), "+v"(ssq[1][3]));
; template <class Epi, class Sched, bool ALIGN_EPI = false, bool SP2 = false>
; __device__ __forceinline__ void gemm_phase(PG8_LAS unsigned char* lds, const Gemm g, const Sched& S, const Epi& E) {
;     ...
;             PG8_LDB(B0, 0, 0); PG8_LDB(B1, 0, 1); PG8_SCHED; PG8_LDA(At, 0, 0); PG8_STAGE(PG8_SA(1, 1), a1 + hstep, voffA);
;             PG8_WAIT_V(8); PG8_WAIT_L(0); PG8_BAR; PG8_MMA(0, 0, At, B0); PG8_MMA(0, 1, At, B1); PG8_BAR; PG8_SCHED;
.LBB0_641:
	s_ashr_i32 s45, s44, 31
	s_lshl_b64 s[46:47], s[44:45], 19
	s_add_u32 s46, s94, s46
	s_addc_u32 s47, s95, s47
	s_and_b64 s[48:49], s[40:41], exec
	s_cselect_b32 s26, s47, s53
	s_cselect_b32 s33, s46, s52
	s_ashr_i32 s43, s42, 31
	s_lshl_b64 s[48:49], s[42:43], 19
	s_add_u32 s48, s28, s48
	s_addc_u32 s49, s58, s49
	s_and_b64 s[56:57], s[40:41], exec
	s_cselect_b32 s43, s49, s55
	s_cselect_b32 s45, s48, s54
	s_add_u32 s52, s52, 0x40080
	s_addc_u32 s53, s53, 0
	s_add_u32 s51, s54, 0x100
	s_addc_u32 s70, s55, 0
	s_mov_b32 s71, -2
	s_lshl_b32 s76, s50, 8
	s_add_i32 s76, s76, s64
	v_add_lshl_u32 v229, v144, s76, 2
	global_load_dword v220, v229, s[4:5]
	global_load_dword v221, v229, s[4:5] offset:64
	global_load_dword v248, v229, s[4:5] offset:128
	global_load_dword v249, v229, s[4:5] offset:192
	global_load_dword v250, v229, s[4:5] offset:512
	global_load_dword v251, v229, s[4:5] offset:576
	global_load_dword v252, v229, s[4:5] offset:640
	global_load_dword v253, v229, s[4:5] offset:704
	s_add_u32 s54, s52, 0xfffc0080
	s_addc_u32 s55, s53, -1
	s_add_i32 s76, 0, 0x10000
	s_cmp_eq_u32 s71, 12
	s_cselect_b32 s57, s26, s55
	s_cselect_b32 s56, s33, s54
	s_cselect_b32 s55, s43, s70
	s_cselect_b32 s54, s45, s51
	s_add_i32 s88, 0, 0x14000
	v_add_u32_e32 v156, s76, v146
	v_add_u32_e32 v172, s88, v146
	ds_read_b128 v[140:143], v156
	ds_read_b128 v[148:151], v156 offset:1024
	ds_read_b128 v[152:155], v156 offset:2048
	ds_read_b128 v[156:159], v156 offset:3072
	ds_read_b128 v[160:163], v172
	ds_read_b128 v[164:167], v172 offset:1024
	ds_read_b128 v[168:171], v172 offset:2048
	ds_read_b128 v[172:175], v172 offset:3072
	v_lshl_add_u64 v[238:239], s[52:53], 0, v[136:137]
	s_add_i32 m0, s60, 0xc000
	ds_read_b128 v[176:179], v147
	ds_read_b128 v[180:183], v147 offset:1024
	ds_read_b128 v[184:187], v147 offset:2048
	ds_read_b128 v[188:191], v147 offset:3072
	ds_read_b128 v[192:195], v147 offset:4096
	ds_read_b128 v[208:211], v147 offset:5120
	ds_read_b128 v[230:233], v147 offset:6144
	ds_read_b128 v[234:237], v147 offset:7168
	global_load_lds_dwordx4 v[238:239], off
	v_lshl_add_u64 v[238:239], s[52:53], 0, v[138:139]
	s_add_i32 m0, s60, 0xe000
	s_nop 0
	global_load_lds_dwordx4 v[238:239], off
	s_waitcnt vmcnt(16)
	s_waitcnt lgkmcnt(0)
	s_barrier
	s_setprio 1
	s_waitcnt lgkmcnt(0)
	v_mfma_f32_16x16x32_bf16 v[128:131], v[140:143], v[176:179], 0
	v_mfma_f32_16x16x32_bf16 v[124:127], v[152:155], v[176:179], 0
	v_mfma_f32_16x16x32_bf16 v[112:115], v[140:143], v[184:187], 0
	v_mfma_f32_16x16x32_bf16 v[108:111], v[152:155], v[184:187], 0
	v_mfma_f32_16x16x32_bf16 v[96:99], v[140:143], v[192:195], 0
	v_mfma_f32_16x16x32_bf16 v[92:95], v[152:155], v[192:195], 0
	v_mfma_f32_16x16x32_bf16 v[80:83], v[140:143], v[230:233], 0
	v_mfma_f32_16x16x32_bf16 v[76:79], v[152:155], v[230:233], 0
	v_mfma_f32_16x16x32_bf16 v[128:131], v[148:151], v[180:183], v[128:131]
	v_mfma_f32_16x16x32_bf16 v[124:127], v[156:159], v[180:183], v[124:127]
	v_mfma_f32_16x16x32_bf16 v[112:115], v[148:151], v[188:191], v[112:115]
	v_mfma_f32_16x16x32_bf16 v[108:111], v[156:159], v[188:191], v[108:111]
	v_mfma_f32_16x16x32_bf16 v[96:99], v[148:151], v[208:211], v[96:99]
	v_mfma_f32_16x16x32_bf16 v[92:95], v[156:159], v[208:211], v[92:95]
	v_mfma_f32_16x16x32_bf16 v[80:83], v[148:151], v[234:237], v[80:83]
	v_mfma_f32_16x16x32_bf16 v[76:79], v[156:159], v[234:237], v[76:79]
	s_setprio 0
	s_setprio 1
	v_mfma_f32_16x16x32_bf16 v[120:123], v[160:163], v[176:179], 0
	v_mfma_f32_16x16x32_bf16 v[116:119], v[168:171], v[176:179], 0
	v_mfma_f32_16x16x32_bf16 v[104:107], v[160:163], v[184:187], 0
	v_mfma_f32_16x16x32_bf16 v[100:103], v[168:171], v[184:187], 0
	v_mfma_f32_16x16x32_bf16 v[88:91], v[160:163], v[192:195], 0
	v_mfma_f32_16x16x32_bf16 v[84:87], v[168:171], v[192:195], 0
	v_mfma_f32_16x16x32_bf16 v[72:75], v[160:163], v[230:233], 0
	v_mfma_f32_16x16x32_bf16 v[68:71], v[168:171], v[230:233], 0
	v_mfma_f32_16x16x32_bf16 v[120:123], v[164:167], v[180:183], v[120:123]
	v_mfma_f32_16x16x32_bf16 v[116:119], v[172:175], v[180:183], v[116:119]
	v_mfma_f32_16x16x32_bf16 v[104:107], v[164:167], v[188:191], v[104:107]
	v_mfma_f32_16x16x32_bf16 v[100:103], v[172:175], v[188:191], v[100:103]
	v_mfma_f32_16x16x32_bf16 v[88:91], v[164:167], v[208:211], v[88:91]
	v_mfma_f32_16x16x32_bf16 v[84:87], v[172:175], v[208:211], v[84:87]
	v_mfma_f32_16x16x32_bf16 v[72:75], v[164:167], v[234:237], v[72:75]
	v_mfma_f32_16x16x32_bf16 v[68:71], v[172:175], v[234:237], v[68:71]
	s_setprio 0
	s_barrier
	s_add_i32 s76, s76, s59
	v_lshl_add_u64 v[238:239], s[54:55], 0, v[2:3]
	s_mov_b32 m0, s76
	ds_read_b128 v[176:179], v147 offset:16384
	ds_read_b128 v[180:183], v147 offset:17408
	ds_read_b128 v[184:187], v147 offset:18432
	ds_read_b128 v[188:191], v147 offset:19456
	ds_read_b128 v[192:195], v147 offset:20480
	ds_read_b128 v[208:211], v147 offset:21504
	ds_read_b128 v[230:233], v147 offset:22528
	ds_read_b128 v[234:237], v147 offset:23552
	global_load_lds_dwordx4 v[238:239], off
	s_add_i32 m0, s76, 0x2000
	s_add_u32 s76, s54, 0x40000
	v_lshl_add_u64 v[240:241], s[54:55], 0, v[134:135]
	s_addc_u32 s77, s55, 0
	s_add_i32 s88, s88, s59
	global_load_lds_dwordx4 v[240:241], off
	v_lshl_add_u64 v[242:243], s[76:77], 0, v[2:3]
	s_mov_b32 m0, s88
	v_lshl_add_u64 v[244:245], s[56:57], 0, v[132:133]
	global_load_lds_dwordx4 v[242:243], off
	v_lshl_add_u64 v[242:243], s[76:77], 0, v[134:135]
	s_add_i32 m0, s88, 0x2000
	s_nop 0
	global_load_lds_dwordx4 v[242:243], off
	v_lshl_add_u64 v[242:243], s[56:57], 0, v[0:1]
	s_mov_b32 m0, s60
	s_nop 0
	global_load_lds_dwordx4 v[242:243], off
	s_mov_b32 m0, s61
	s_nop 0
	global_load_lds_dwordx4 v[244:245], off
	s_waitcnt vmcnt(16)
	s_waitcnt lgkmcnt(0)
	s_barrier
; #define PG8_STAGE(bufoff, gbase, voff) do { _Pragma("unroll") for (int _i = 0; _i < 2; ++_i) \
;         __builtin_amdgcn_global_load_lds((const unsigned*)((const char*)(gbase) + (voff)[_i]), (PG8_LAS unsigned*)(lds + (bufoff) + ldsw + _i * 8192), 16, 0, 0); } while (0)
; #define PG8_LDA(dst, b, h) do { _Pragma("unroll") for (int m = 0; m < 4; ++m) _Pragma("unroll") for (int k = 0; k < 2; ++k) dst[m][k] = *(const PG8_LAS bf16x8*)(lds + PG8_SA(b, h) + aoff + m * 2048 + k * 1024); } while (0)
; #define PG8_LDB(dst, b, h) do { _Pragma("unroll") for (int n = 0; n < 2; ++n) _Pragma("unroll") for (int k = 0; k < 2; ++k) dst[n][k] = *(const PG8_LAS bf16x8*)(lds + PG8_SB(b, h) + boff + n * 2048 + k * 1024); } while (0)
; #define PG8_MMA(ai, bj, At, Bt) do { __builtin_amdgcn_s_setprio(1); _Pragma("unroll") for (int m = 0; m < 4; ++m) _Pragma("unroll") for (int n = 0; n < 2; ++n) _Pragma("unroll") for (int k = 0; k < 2; ++k) \
;         acc[ai][bj][m][n] = __builtin_amdgcn_mfma_f32_16x16x32_bf16(Bt[n][k], At[m][k], acc[ai][bj][m][n], 0, 0, 0); __builtin_amdgcn_s_setprio(0); } while (0)
; #define PG8_WAIT_V(n) asm volatile("s_waitcnt vmcnt(" #n ")" ::: "memory")
; #define PG8_WAIT_L(n) asm volatile("s_waitcnt lgkmcnt(" #n ")" ::: "memory")
; #define PG8_BAR __builtin_amdgcn_s_barrier()
; #define PG8_SCHED __builtin_amdgcn_sched_barrier(0)
; template <class Epi, class Sched, bool ALIGN_EPI = false, bool SP2 = false>
; __device__ __forceinline__ void gemm_phase(PG8_LAS unsigned char* lds, const Gemm g, const Sched& S, const Epi& E) {
;     ...
;             PG8_LDA(At, 0, 1); PG8_STAGE(PG8_SB(0, 0), b2, voffB); PG8_STAGE(PG8_SB(0, 1), b2 + hstep, voffB); PG8_STAGE(PG8_SA(0, 0), a2, voffA);
;             PG8_WAIT_V(8); PG8_WAIT_L(0); PG8_BAR; PG8_MMA(1, 0, At, B0); PG8_MMA(1, 1, At, B1); PG8_BAR; PG8_SCHED;
;             PG8_LDB(B0, 1, 0); PG8_LDB(B1, 1, 1); PG8_SCHED; PG8_LDA(At, 1, 0); PG8_STAGE(PG8_SA(0, 1), a2 + hstep, voffA);
;             PG8_WAIT_V(8); PG8_WAIT_L(0); PG8_BAR; PG8_MMA(0, 0, At, B0); PG8_MMA(0, 1, At, B1); PG8_BAR; PG8_SCHED;
	s_setprio 1
	s_waitcnt lgkmcnt(0)
	v_mfma_f32_16x16x32_bf16 v[64:67], v[140:143], v[176:179], 0
	v_mfma_f32_16x16x32_bf16 v[60:63], v[152:155], v[176:179], 0
	v_mfma_f32_16x16x32_bf16 v[48:51], v[140:143], v[184:187], 0
	v_mfma_f32_16x16x32_bf16 v[44:47], v[152:155], v[184:187], 0
	v_mfma_f32_16x16x32_bf16 v[32:35], v[140:143], v[192:195], 0
	v_mfma_f32_16x16x32_bf16 v[28:31], v[152:155], v[192:195], 0
	v_mfma_f32_16x16x32_bf16 v[16:19], v[140:143], v[230:233], 0
	v_mfma_f32_16x16x32_bf16 v[12:15], v[152:155], v[230:233], 0
	v_mfma_f32_16x16x32_bf16 v[64:67], v[148:151], v[180:183], v[64:67]
	v_mfma_f32_16x16x32_bf16 v[60:63], v[156:159], v[180:183], v[60:63]
	v_mfma_f32_16x16x32_bf16 v[48:51], v[148:151], v[188:191], v[48:51]
	v_mfma_f32_16x16x32_bf16 v[44:47], v[156:159], v[188:191], v[44:47]
	v_mfma_f32_16x16x32_bf16 v[32:35], v[148:151], v[208:211], v[32:35]
	v_mfma_f32_16x16x32_bf16 v[28:31], v[156:159], v[208:211], v[28:31]
	v_mfma_f32_16x16x32_bf16 v[16:19], v[148:151], v[234:237], v[16:19]
	v_mfma_f32_16x16x32_bf16 v[12:15], v[156:159], v[234:237], v[12:15]
	s_setprio 0
	s_setprio 1
	v_mfma_f32_16x16x32_bf16 v[56:59], v[160:163], v[176:179], 0
	v_mfma_f32_16x16x32_bf16 v[52:55], v[168:171], v[176:179], 0
	v_mfma_f32_16x16x32_bf16 v[40:43], v[160:163], v[184:187], 0
	v_mfma_f32_16x16x32_bf16 v[36:39], v[168:171], v[184:187], 0
	v_mfma_f32_16x16x32_bf16 v[24:27], v[160:163], v[192:195], 0
	v_mfma_f32_16x16x32_bf16 v[20:23], v[168:171], v[192:195], 0
	v_mfma_f32_16x16x32_bf16 v[8:11], v[160:163], v[230:233], 0
	v_mfma_f32_16x16x32_bf16 v[4:7], v[168:171], v[230:233], 0
	v_mfma_f32_16x16x32_bf16 v[56:59], v[164:167], v[180:183], v[56:59]
	v_mfma_f32_16x16x32_bf16 v[52:55], v[172:175], v[180:183], v[52:55]
	v_mfma_f32_16x16x32_bf16 v[40:43], v[164:167], v[188:191], v[40:43]
	v_mfma_f32_16x16x32_bf16 v[36:39], v[172:175], v[188:191], v[36:39]
	v_mfma_f32_16x16x32_bf16 v[24:27], v[164:167], v[208:211], v[24:27]
	v_mfma_f32_16x16x32_bf16 v[20:23], v[172:175], v[208:211], v[20:23]
	v_mfma_f32_16x16x32_bf16 v[8:11], v[164:167], v[234:237], v[8:11]
	v_mfma_f32_16x16x32_bf16 v[4:7], v[172:175], v[234:237], v[4:7]
	s_setprio 0
	s_barrier
	s_add_i32 s76, 0, 0x18000
	s_add_i32 s77, 0, 0x1c000
	v_add_u32_e32 v156, s76, v146
	v_add_u32_e32 v172, s77, v146
	ds_read_b128 v[140:143], v156
	ds_read_b128 v[148:151], v156 offset:1024
	ds_read_b128 v[152:155], v156 offset:2048
	ds_read_b128 v[156:159], v156 offset:3072
	ds_read_b128 v[160:163], v172
	ds_read_b128 v[164:167], v172 offset:1024
	ds_read_b128 v[168:171], v172 offset:2048
	ds_read_b128 v[172:175], v172 offset:3072
	s_add_u32 s56, s56, 0x40000
	s_addc_u32 s57, s57, 0
	s_mov_b32 m0, s62
	v_lshl_add_u64 v[246:247], s[56:57], 0, v[0:1]
	ds_read_b128 v[176:179], v147 offset:32768
	ds_read_b128 v[180:183], v147 offset:33792
	ds_read_b128 v[184:187], v147 offset:34816
	ds_read_b128 v[188:191], v147 offset:35840
	ds_read_b128 v[192:195], v147 offset:36864
	ds_read_b128 v[208:211], v147 offset:37888
	ds_read_b128 v[230:233], v147 offset:38912
	ds_read_b128 v[234:237], v147 offset:39936
	global_load_lds_dwordx4 v[246:247], off
	v_lshl_add_u64 v[246:247], s[56:57], 0, v[132:133]
	s_mov_b32 m0, s63
	s_nop 0
	global_load_lds_dwordx4 v[246:247], off
	s_waitcnt vmcnt(8)
	s_waitcnt lgkmcnt(0)
	s_barrier
	s_setprio 1
	s_waitcnt lgkmcnt(0)
	v_mfma_f32_16x16x32_bf16 v[128:131], v[140:143], v[176:179], v[128:131]
	v_mfma_f32_16x16x32_bf16 v[124:127], v[152:155], v[176:179], v[124:127]
	v_mfma_f32_16x16x32_bf16 v[112:115], v[140:143], v[184:187], v[112:115]
	v_mfma_f32_16x16x32_bf16 v[108:111], v[152:155], v[184:187], v[108:111]
	v_mfma_f32_16x16x32_bf16 v[96:99], v[140:143], v[192:195], v[96:99]
	v_mfma_f32_16x16x32_bf16 v[92:95], v[152:155], v[192:195], v[92:95]
	v_mfma_f32_16x16x32_bf16 v[80:83], v[140:143], v[230:233], v[80:83]
	v_mfma_f32_16x16x32_bf16 v[76:79], v[152:155], v[230:233], v[76:79]
	v_mfma_f32_16x16x32_bf16 v[128:131], v[148:151], v[180:183], v[128:131]
	v_mfma_f32_16x16x32_bf16 v[124:127], v[156:159], v[180:183], v[124:127]
	v_mfma_f32_16x16x32_bf16 v[112:115], v[148:151], v[188:191], v[112:115]
	v_mfma_f32_16x16x32_bf16 v[108:111], v[156:159], v[188:191], v[108:111]
	v_mfma_f32_16x16x32_bf16 v[96:99], v[148:151], v[208:211], v[96:99]
	v_mfma_f32_16x16x32_bf16 v[92:95], v[156:159], v[208:211], v[92:95]
	v_mfma_f32_16x16x32_bf16 v[80:83], v[148:151], v[234:237], v[80:83]
	v_mfma_f32_16x16x32_bf16 v[76:79], v[156:159], v[234:237], v[76:79]
	s_setprio 0
	s_setprio 1
	v_mfma_f32_16x16x32_bf16 v[120:123], v[160:163], v[176:179], v[120:123]
	v_mfma_f32_16x16x32_bf16 v[116:119], v[168:171], v[176:179], v[116:119]
	v_mfma_f32_16x16x32_bf16 v[104:107], v[160:163], v[184:187], v[104:107]
	v_mfma_f32_16x16x32_bf16 v[100:103], v[168:171], v[184:187], v[100:103]
	v_mfma_f32_16x16x32_bf16 v[88:91], v[160:163], v[192:195], v[88:91]
	v_mfma_f32_16x16x32_bf16 v[84:87], v[168:171], v[192:195], v[84:87]
	v_mfma_f32_16x16x32_bf16 v[72:75], v[160:163], v[230:233], v[72:75]
	v_mfma_f32_16x16x32_bf16 v[68:71], v[168:171], v[230:233], v[68:71]
	v_mfma_f32_16x16x32_bf16 v[120:123], v[164:167], v[180:183], v[120:123]
	v_mfma_f32_16x16x32_bf16 v[116:119], v[172:175], v[180:183], v[116:119]
	v_mfma_f32_16x16x32_bf16 v[104:107], v[164:167], v[188:191], v[104:107]
	v_mfma_f32_16x16x32_bf16 v[100:103], v[172:175], v[188:191], v[100:103]
	v_mfma_f32_16x16x32_bf16 v[88:91], v[164:167], v[208:211], v[88:91]
	v_mfma_f32_16x16x32_bf16 v[84:87], v[172:175], v[208:211], v[84:87]
	v_mfma_f32_16x16x32_bf16 v[72:75], v[164:167], v[234:237], v[72:75]
	v_mfma_f32_16x16x32_bf16 v[68:71], v[172:175], v[234:237], v[68:71]
	s_setprio 0
	s_barrier
; #define PG8_STAGE(bufoff, gbase, voff) do { _Pragma("unroll") for (int _i = 0; _i < 2; ++_i) \
;         __builtin_amdgcn_global_load_lds((const unsigned*)((const char*)(gbase) + (voff)[_i]), (PG8_LAS unsigned*)(lds + (bufoff) + ldsw + _i * 8192), 16, 0, 0); } while (0)
; #define PG8_LDA(dst, b, h) do { _Pragma("unroll") for (int m = 0; m < 4; ++m) _Pragma("unroll") for (int k = 0; k < 2; ++k) dst[m][k] = *(const PG8_LAS bf16x8*)(lds + PG8_SA(b, h) + aoff + m * 2048 + k * 1024); } while (0)
; #define PG8_MMA(ai, bj, At, Bt) do { __builtin_amdgcn_s_setprio(1); _Pragma("unroll") for (int m = 0; m < 4; ++m) _Pragma("unroll") for (int n = 0; n < 2; ++n) _Pragma("unroll") for (int k = 0; k < 2; ++k) \
;         acc[ai][bj][m][n] = __builtin_amdgcn_mfma_f32_16x16x32_bf16(Bt[n][k], At[m][k], acc[ai][bj][m][n], 0, 0, 0); __builtin_amdgcn_s_setprio(0); } while (0)
; #define PG8_WAIT_V(n) asm volatile("s_waitcnt vmcnt(" #n ")" ::: "memory")
; #define PG8_WAIT_L(n) asm volatile("s_waitcnt lgkmcnt(" #n ")" ::: "memory")
; #define PG8_BAR __builtin_amdgcn_s_barrier()
; #define PG8_SCHED __builtin_amdgcn_sched_barrier(0)
; template <class Epi, class Sched, bool ALIGN_EPI = false, bool SP2 = false>
; __device__ __forceinline__ void gemm_phase(PG8_LAS unsigned char* lds, const Gemm g, const Sched& S, const Epi& E) {
;     ...
;             PG8_LDA(At, 1, 1); PG8_STAGE(PG8_SB(1, 0), b3, voffB); PG8_STAGE(PG8_SB(1, 1), b3 + hstep, voffB); PG8_STAGE(PG8_SA(1, 0), a3, voffA);
;             PG8_WAIT_V(8); PG8_WAIT_L(0); PG8_BAR; PG8_MMA(1, 0, At, B0); PG8_MMA(1, 1, At, B1); PG8_BAR; PG8_SCHED;
	s_add_i32 s56, s76, s59
	v_lshl_add_u64 v[238:239], v[238:239], 0, s[36:37]
	s_mov_b32 m0, s56
	ds_read_b128 v[176:179], v147 offset:49152
	ds_read_b128 v[180:183], v147 offset:50176
	ds_read_b128 v[184:187], v147 offset:51200
	ds_read_b128 v[188:191], v147 offset:52224
	ds_read_b128 v[192:195], v147 offset:53248
	ds_read_b128 v[208:211], v147 offset:54272
	ds_read_b128 v[230:233], v147 offset:55296
	ds_read_b128 v[234:237], v147 offset:56320
	global_load_lds_dwordx4 v[238:239], off
	s_add_i32 m0, s56, 0x2000
	s_add_u32 s54, s54, 0x40080
	v_lshl_add_u64 v[238:239], v[240:241], 0, s[36:37]
	s_addc_u32 s55, s55, 0
	s_add_i32 s56, s77, s59
	global_load_lds_dwordx4 v[238:239], off
	v_lshl_add_u64 v[238:239], s[54:55], 0, v[2:3]
	s_mov_b32 m0, s56
	s_nop 0
	global_load_lds_dwordx4 v[238:239], off
	v_lshl_add_u64 v[238:239], s[54:55], 0, v[134:135]
	s_add_i32 m0, s56, 0x2000
	s_nop 0
	global_load_lds_dwordx4 v[238:239], off
	v_lshl_add_u64 v[238:239], v[242:243], 0, s[36:37]
	s_mov_b32 m0, s66
	s_nop 0
	global_load_lds_dwordx4 v[238:239], off
	v_lshl_add_u64 v[238:239], v[244:245], 0, s[36:37]
	s_mov_b32 m0, s67
	s_nop 0
	global_load_lds_dwordx4 v[238:239], off
	s_waitcnt vmcnt(8)
	s_waitcnt lgkmcnt(0)
	s_barrier
	s_setprio 1
	s_waitcnt lgkmcnt(0)
	v_mfma_f32_16x16x32_bf16 v[64:67], v[140:143], v[176:179], v[64:67]
	v_mfma_f32_16x16x32_bf16 v[60:63], v[152:155], v[176:179], v[60:63]
	v_mfma_f32_16x16x32_bf16 v[48:51], v[140:143], v[184:187], v[48:51]
	v_mfma_f32_16x16x32_bf16 v[44:47], v[152:155], v[184:187], v[44:47]
	v_mfma_f32_16x16x32_bf16 v[32:35], v[140:143], v[192:195], v[32:35]
	v_mfma_f32_16x16x32_bf16 v[28:31], v[152:155], v[192:195], v[28:31]
	v_mfma_f32_16x16x32_bf16 v[16:19], v[140:143], v[230:233], v[16:19]
	v_mfma_f32_16x16x32_bf16 v[12:15], v[152:155], v[230:233], v[12:15]
	v_mfma_f32_16x16x32_bf16 v[64:67], v[148:151], v[180:183], v[64:67]
	v_mfma_f32_16x16x32_bf16 v[60:63], v[156:159], v[180:183], v[60:63]
	v_mfma_f32_16x16x32_bf16 v[48:51], v[148:151], v[188:191], v[48:51]
	v_mfma_f32_16x16x32_bf16 v[44:47], v[156:159], v[188:191], v[44:47]
	v_mfma_f32_16x16x32_bf16 v[32:35], v[148:151], v[208:211], v[32:35]
	v_mfma_f32_16x16x32_bf16 v[28:31], v[156:159], v[208:211], v[28:31]
	v_mfma_f32_16x16x32_bf16 v[16:19], v[148:151], v[234:237], v[16:19]
	v_mfma_f32_16x16x32_bf16 v[12:15], v[156:159], v[234:237], v[12:15]
	s_setprio 0
	s_setprio 1
	v_mfma_f32_16x16x32_bf16 v[56:59], v[160:163], v[176:179], v[56:59]
	v_mfma_f32_16x16x32_bf16 v[52:55], v[168:171], v[176:179], v[52:55]
	v_mfma_f32_16x16x32_bf16 v[40:43], v[160:163], v[184:187], v[40:43]
	v_mfma_f32_16x16x32_bf16 v[36:39], v[168:171], v[184:187], v[36:39]
	v_mfma_f32_16x16x32_bf16 v[24:27], v[160:163], v[192:195], v[24:27]
	v_mfma_f32_16x16x32_bf16 v[20:23], v[168:171], v[192:195], v[20:23]
	v_mfma_f32_16x16x32_bf16 v[8:11], v[160:163], v[230:233], v[8:11]
	v_mfma_f32_16x16x32_bf16 v[4:7], v[168:171], v[230:233], v[4:7]
	v_mfma_f32_16x16x32_bf16 v[56:59], v[164:167], v[180:183], v[56:59]
	v_mfma_f32_16x16x32_bf16 v[52:55], v[172:175], v[180:183], v[52:55]
	v_mfma_f32_16x16x32_bf16 v[40:43], v[164:167], v[188:191], v[40:43]
	v_mfma_f32_16x16x32_bf16 v[36:39], v[172:175], v[188:191], v[36:39]
	v_mfma_f32_16x16x32_bf16 v[24:27], v[164:167], v[208:211], v[24:27]
	v_mfma_f32_16x16x32_bf16 v[20:23], v[172:175], v[208:211], v[20:23]
	v_mfma_f32_16x16x32_bf16 v[8:11], v[164:167], v[234:237], v[8:11]
	v_mfma_f32_16x16x32_bf16 v[4:7], v[172:175], v[234:237], v[4:7]
	s_setprio 0
	s_barrier
	s_add_i32 s71, s71, 2
	s_add_u32 s52, s52, 0x100
	s_addc_u32 s53, s53, 0
	s_add_u32 s51, s51, 0x100
	s_addc_u32 s70, s70, 0

; __device__ __forceinline__ unsigned cvt_pk_bf16(float lo, float hi) { unsigned r; asm volatile("v_cvt_pk_bf16_f32 %0, %1, %2" : "=v"(r) : "v"(lo), "v"(hi)); return r; }
; __device__ __forceinline__ float rstd_of(float ss) { return __builtin_amdgcn_rsqf(ss * (1.0f / 1024.0f) + RMS_EPS_F); }
; __device__ __forceinline__ float silu_mul(float g, float u) { return g * __builtin_amdgcn_rcpf(1.0f + __builtin_amdgcn_exp2f(-1.4426950408889634f * g)) * u; }
;     __device__ __forceinline__ void operator()(const f32x4 (&acc)[2][2][4][2], const Unit& u, int wr, int wc, int fr_in, int fq_in) const {
;     ...
;         const int row0 = u.pm * BM + wr * 64 + fr, col0 = u.pn * HALF + wc * 32 + 8 * fq;
;         float ssq[2][4];
; #pragma unroll
;         for (int ai = 0; ai < 2; ++ai)
; #pragma unroll
;             for (int m = 0; m < 4; ++m) ssq[ai][m] = rowss[row0 + ai * HALF + m * 16];
;         asm volatile("" : "+v"(ssq[0][0]), "+v"(ssq[0][1]), "+v"(ssq[0][2]), "+v"(ssq[0][3]), "+v"(ssq[1][0]), "+v"(ssq[1][1]), "+v"(ssq[1][2]), "+v"(ssq[1][3]));
; #pragma unroll
;         for (int ai = 0; ai < 2; ++ai)
; #pragma unroll
;             for (int m = 0; m < 4; ++m) { const int row = row0 + ai * HALF + m * 16; const float rs = rstd_of(ssq[ai][m]);
;                 const f32x4 g0 = acc[ai][0][m][0] * rs, g1 = acc[ai][0][m][1] * rs, u0 = acc[ai][1][m][0] * rs, u1 = acc[ai][1][m][1] * rs;
;                 u32x4 w; w.x = cvt_pk_bf16(silu_mul(g0[0], u0[0]), silu_mul(g0[1], u0[1])); w.y = cvt_pk_bf16(silu_mul(g0[2], u0[2]), silu_mul(g0[3], u0[3]));
;                 w.z = cvt_pk_bf16(silu_mul(g1[0], u1[0]), silu_mul(g1[1], u1[1])); w.w = cvt_pk_bf16(silu_mul(g1[2], u1[2]), silu_mul(g1[3], u1[3]));
;                 *(u32x4*)(act + (size_t)row * 4096 + col0) = w; }
.LBB0_645:
	s_lshl_b32 s26, s50, 8
	s_add_i32 s26, s26, s64
	s_lshl_b32 s22, s22, 7
	v_add_u32_e32 v142, s26, v144
	s_or_b32 s22, s22, s65
	v_lshl_add_u32 v140, v145, 3, s22
	v_lshlrev_b32_e32 v172, 13, v142
	s_mov_b64 s[50:51], -1
	v_lshl_add_u32 v172, v140, 1, v172
	v_fmamk_f32 v169, v220, 0x3a800000, v213
	v_rsq_f32_e32 v170, v169
	v_mov_b32_e32 v174, v172
	v_mul_f32_e32 v168, 0xbfb8aa3b, v170
	v_mul_f32_e32 v160, v168, v128
	v_mul_f32_e32 v161, v168, v129
	v_mul_f32_e32 v162, v168, v130
	v_mul_f32_e32 v163, v168, v131
	v_mul_f32_e32 v164, v168, v124
	v_mul_f32_e32 v165, v168, v125
	v_mul_f32_e32 v166, v168, v126
	v_mul_f32_e32 v167, v168, v127
	v_exp_f32_e32 v160, v160
	v_exp_f32_e32 v161, v161
	v_exp_f32_e32 v162, v162
	v_exp_f32_e32 v163, v163
	v_exp_f32_e32 v164, v164
	v_exp_f32_e32 v165, v165
	v_exp_f32_e32 v166, v166
	v_exp_f32_e32 v167, v167
	v_fma_f32 v160, v160, v169, v169
	v_fma_f32 v161, v161, v169, v169
	v_fma_f32 v162, v162, v169, v169
	v_fma_f32 v163, v163, v169, v169
	v_fma_f32 v164, v164, v169, v169
	v_fma_f32 v165, v165, v169, v169
	v_fma_f32 v166, v166, v169, v169
	v_fma_f32 v167, v167, v169, v169
	v_rcp_f32_e32 v160, v160
	v_rcp_f32_e32 v161, v161
	v_rcp_f32_e32 v162, v162
	v_rcp_f32_e32 v163, v163
	v_rcp_f32_e32 v164, v164
	v_rcp_f32_e32 v165, v165
	v_rcp_f32_e32 v166, v166
	v_rcp_f32_e32 v167, v167
	v_pk_mul_f32 v[128:129], v[128:129], v[120:121]
	v_pk_mul_f32 v[130:131], v[130:131], v[122:123]
	v_pk_mul_f32 v[124:125], v[124:125], v[116:117]
	v_pk_mul_f32 v[126:127], v[126:127], v[118:119]
	v_pk_mul_f32 v[128:129], v[128:129], v[160:161]
	v_pk_mul_f32 v[130:131], v[130:131], v[162:163]
	v_pk_mul_f32 v[124:125], v[124:125], v[164:165]
	v_pk_mul_f32 v[126:127], v[126:127], v[166:167]
	v_cvt_pk_bf16_f32 v120, v128, v129
	v_cvt_pk_bf16_f32 v121, v130, v131
	v_cvt_pk_bf16_f32 v122, v124, v125
	v_cvt_pk_bf16_f32 v123, v126, v127
	global_store_dwordx4 v174, v[120:123], s[92:93]
	v_fmamk_f32 v169, v221, 0x3a800000, v213
	v_rsq_f32_e32 v170, v169
	v_add_u32_e32 v174, 0x20000, v172
	v_mul_f32_e32 v168, 0xbfb8aa3b, v170
	v_mul_f32_e32 v160, v168, v112
	v_mul_f32_e32 v161, v168, v113
	v_mul_f32_e32 v162, v168, v114
	v_mul_f32_e32 v163, v168, v115
	v_mul_f32_e32 v164, v168, v108
	v_mul_f32_e32 v165, v168, v109
	v_mul_f32_e32 v166, v168, v110
	v_mul_f32_e32 v167, v168, v111
	v_exp_f32_e32 v160, v160
	v_exp_f32_e32 v161, v161
	v_exp_f32_e32 v162, v162
	v_exp_f32_e32 v163, v163
	v_exp_f32_e32 v164, v164
	v_exp_f32_e32 v165, v165
	v_exp_f32_e32 v166, v166
	v_exp_f32_e32 v167, v167
	v_fma_f32 v160, v160, v169, v169
	v_fma_f32 v161, v161, v169, v169
	v_fma_f32 v162, v162, v169, v169
	v_fma_f32 v163, v163, v169, v169
	v_fma_f32 v164, v164, v169, v169
	v_fma_f32 v165, v165, v169, v169
	v_fma_f32 v166, v166, v169, v169
	v_fma_f32 v167, v167, v169, v169
	v_rcp_f32_e32 v160, v160
	v_rcp_f32_e32 v161, v161
	v_rcp_f32_e32 v162, v162
	v_rcp_f32_e32 v163, v163
	v_rcp_f32_e32 v164, v164
	v_rcp_f32_e32 v165, v165
	v_rcp_f32_e32 v166, v166
	v_rcp_f32_e32 v167, v167
	v_pk_mul_f32 v[112:113], v[112:113], v[104:105]
	v_pk_mul_f32 v[114:115], v[114:115], v[106:107]
	v_pk_mul_f32 v[108:109], v[108:109], v[100:101]
	v_pk_mul_f32 v[110:111], v[110:111], v[102:103]
	v_pk_mul_f32 v[112:113], v[112:113], v[160:161]
	v_pk_mul_f32 v[114:115], v[114:115], v[162:163]
	v_pk_mul_f32 v[108:109], v[108:109], v[164:165]
	v_pk_mul_f32 v[110:111], v[110:111], v[166:167]
	v_cvt_pk_bf16_f32 v104, v112, v113
	v_cvt_pk_bf16_f32 v105, v114, v115
	v_cvt_pk_bf16_f32 v106, v108, v109
	v_cvt_pk_bf16_f32 v107, v110, v111
	global_store_dwordx4 v174, v[104:107], s[92:93]
	v_fmamk_f32 v169, v248, 0x3a800000, v213
	v_rsq_f32_e32 v170, v169
	v_add_u32_e32 v174, 0x40000, v172
	v_mul_f32_e32 v168, 0xbfb8aa3b, v170
	v_mul_f32_e32 v160, v168, v96
	v_mul_f32_e32 v161, v168, v97
	v_mul_f32_e32 v162, v168, v98
	v_mul_f32_e32 v163, v168, v99
	v_mul_f32_e32 v164, v168, v92
	v_mul_f32_e32 v165, v168, v93
	v_mul_f32_e32 v166, v168, v94
	v_mul_f32_e32 v167, v168, v95
	v_exp_f32_e32 v160, v160
	v_exp_f32_e32 v161, v161
	v_exp_f32_e32 v162, v162
	v_exp_f32_e32 v163, v163
	v_exp_f32_e32 v164, v164
	v_exp_f32_e32 v165, v165
	v_exp_f32_e32 v166, v166
	v_exp_f32_e32 v167, v167
	v_fma_f32 v160, v160, v169, v169
	v_fma_f32 v161, v161, v169, v169
	v_fma_f32 v162, v162, v169, v169
	v_fma_f32 v163, v163, v169, v169
	v_fma_f32 v164, v164, v169, v169
	v_fma_f32 v165, v165, v169, v169
	v_fma_f32 v166, v166, v169, v169
	v_fma_f32 v167, v167, v169, v169
	v_rcp_f32_e32 v160, v160
	v_rcp_f32_e32 v161, v161
	v_rcp_f32_e32 v162, v162
	v_rcp_f32_e32 v163, v163
	v_rcp_f32_e32 v164, v164
	v_rcp_f32_e32 v165, v165
	v_rcp_f32_e32 v166, v166
	v_rcp_f32_e32 v167, v167
	v_pk_mul_f32 v[96:97], v[96:97], v[88:89]
	v_pk_mul_f32 v[98:99], v[98:99], v[90:91]
	v_pk_mul_f32 v[92:93], v[92:93], v[84:85]
	v_pk_mul_f32 v[94:95], v[94:95], v[86:87]
	v_pk_mul_f32 v[96:97], v[96:97], v[160:161]
	v_pk_mul_f32 v[98:99], v[98:99], v[162:163]
	v_pk_mul_f32 v[92:93], v[92:93], v[164:165]
	v_pk_mul_f32 v[94:95], v[94:95], v[166:167]
	v_cvt_pk_bf16_f32 v88, v96, v97
	v_cvt_pk_bf16_f32 v89, v98, v99
	v_cvt_pk_bf16_f32 v90, v92, v93
	v_cvt_pk_bf16_f32 v91, v94, v95
	global_store_dwordx4 v174, v[88:91], s[92:93]
	v_fmamk_f32 v169, v249, 0x3a800000, v213
	v_rsq_f32_e32 v170, v169
	v_add_u32_e32 v174, 0x60000, v172
	v_mul_f32_e32 v168, 0xbfb8aa3b, v170
	v_mul_f32_e32 v160, v168, v80
	v_mul_f32_e32 v161, v168, v81
	v_mul_f32_e32 v162, v168, v82
	v_mul_f32_e32 v163, v168, v83
	v_mul_f32_e32 v164, v168, v76
	v_mul_f32_e32 v165, v168, v77
	v_mul_f32_e32 v166, v168, v78
	v_mul_f32_e32 v167, v168, v79
	v_exp_f32_e32 v160, v160
	v_exp_f32_e32 v161, v161
; __device__ __forceinline__ unsigned cvt_pk_bf16(float lo, float hi) { unsigned r; asm volatile("v_cvt_pk_bf16_f32 %0, %1, %2" : "=v"(r) : "v"(lo), "v"(hi)); return r; }
; __device__ __forceinline__ float rstd_of(float ss) { return __builtin_amdgcn_rsqf(ss * (1.0f / 1024.0f) + RMS_EPS_F); }
; __device__ __forceinline__ float silu_mul(float g, float u) { return g * __builtin_amdgcn_rcpf(1.0f + __builtin_amdgcn_exp2f(-1.4426950408889634f * g)) * u; }
;     __device__ __forceinline__ void operator()(const f32x4 (&acc)[2][2][4][2], const Unit& u, int wr, int wc, int fr_in, int fq_in) const {
;     ...
;             for (int m = 0; m < 4; ++m) { const int row = row0 + ai * HALF + m * 16; const float rs = rstd_of(ssq[ai][m]);
;                 const f32x4 g0 = acc[ai][0][m][0] * rs, g1 = acc[ai][0][m][1] * rs, u0 = acc[ai][1][m][0] * rs, u1 = acc[ai][1][m][1] * rs;
;                 u32x4 w; w.x = cvt_pk_bf16(silu_mul(g0[0], u0[0]), silu_mul(g0[1], u0[1])); w.y = cvt_pk_bf16(silu_mul(g0[2], u0[2]), silu_mul(g0[3], u0[3]));
;                 w.z = cvt_pk_bf16(silu_mul(g1[0], u1[0]), silu_mul(g1[1], u1[1])); w.w = cvt_pk_bf16(silu_mul(g1[2], u1[2]), silu_mul(g1[3], u1[3]));
;                 *(u32x4*)(act + (size_t)row * 4096 + col0) = w; }
	v_exp_f32_e32 v162, v162
	v_exp_f32_e32 v163, v163
	v_exp_f32_e32 v164, v164
	v_exp_f32_e32 v165, v165
	v_exp_f32_e32 v166, v166
	v_exp_f32_e32 v167, v167
	v_fma_f32 v160, v160, v169, v169
	v_fma_f32 v161, v161, v169, v169
	v_fma_f32 v162, v162, v169, v169
	v_fma_f32 v163, v163, v169, v169
	v_fma_f32 v164, v164, v169, v169
	v_fma_f32 v165, v165, v169, v169
	v_fma_f32 v166, v166, v169, v169
	v_fma_f32 v167, v167, v169, v169
	v_rcp_f32_e32 v160, v160
	v_rcp_f32_e32 v161, v161
	v_rcp_f32_e32 v162, v162
	v_rcp_f32_e32 v163, v163
	v_rcp_f32_e32 v164, v164
	v_rcp_f32_e32 v165, v165
	v_rcp_f32_e32 v166, v166
	v_rcp_f32_e32 v167, v167
	v_pk_mul_f32 v[80:81], v[80:81], v[72:73]
	v_pk_mul_f32 v[82:83], v[82:83], v[74:75]
	v_pk_mul_f32 v[76:77], v[76:77], v[68:69]
	v_pk_mul_f32 v[78:79], v[78:79], v[70:71]
	v_pk_mul_f32 v[80:81], v[80:81], v[160:161]
	v_pk_mul_f32 v[82:83], v[82:83], v[162:163]
	v_pk_mul_f32 v[76:77], v[76:77], v[164:165]
	v_pk_mul_f32 v[78:79], v[78:79], v[166:167]
	v_cvt_pk_bf16_f32 v72, v80, v81
	v_cvt_pk_bf16_f32 v73, v82, v83
	v_cvt_pk_bf16_f32 v74, v76, v77
	v_cvt_pk_bf16_f32 v75, v78, v79
	global_store_dwordx4 v174, v[72:75], s[92:93]
	v_fmamk_f32 v169, v250, 0x3a800000, v213
	v_rsq_f32_e32 v170, v169
	v_add_u32_e32 v174, 0x100000, v172
	v_mul_f32_e32 v168, 0xbfb8aa3b, v170
	v_mul_f32_e32 v160, v168, v64
	v_mul_f32_e32 v161, v168, v65
	v_mul_f32_e32 v162, v168, v66
	v_mul_f32_e32 v163, v168, v67
	v_mul_f32_e32 v164, v168, v60
	v_mul_f32_e32 v165, v168, v61
	v_mul_f32_e32 v166, v168, v62
	v_mul_f32_e32 v167, v168, v63
	v_exp_f32_e32 v160, v160
	v_exp_f32_e32 v161, v161
	v_exp_f32_e32 v162, v162
	v_exp_f32_e32 v163, v163
	v_exp_f32_e32 v164, v164
	v_exp_f32_e32 v165, v165
	v_exp_f32_e32 v166, v166
	v_exp_f32_e32 v167, v167
	v_fma_f32 v160, v160, v169, v169
	v_fma_f32 v161, v161, v169, v169
	v_fma_f32 v162, v162, v169, v169
	v_fma_f32 v163, v163, v169, v169
	v_fma_f32 v164, v164, v169, v169
	v_fma_f32 v165, v165, v169, v169
	v_fma_f32 v166, v166, v169, v169
	v_fma_f32 v167, v167, v169, v169
	v_rcp_f32_e32 v160, v160
	v_rcp_f32_e32 v161, v161
	v_rcp_f32_e32 v162, v162
	v_rcp_f32_e32 v163, v163
	v_rcp_f32_e32 v164, v164
	v_rcp_f32_e32 v165, v165
	v_rcp_f32_e32 v166, v166
	v_rcp_f32_e32 v167, v167
	v_pk_mul_f32 v[64:65], v[64:65], v[56:57]
	v_pk_mul_f32 v[66:67], v[66:67], v[58:59]
	v_pk_mul_f32 v[60:61], v[60:61], v[52:53]
	v_pk_mul_f32 v[62:63], v[62:63], v[54:55]
	v_pk_mul_f32 v[64:65], v[64:65], v[160:161]
	v_pk_mul_f32 v[66:67], v[66:67], v[162:163]
	v_pk_mul_f32 v[60:61], v[60:61], v[164:165]
	v_pk_mul_f32 v[62:63], v[62:63], v[166:167]
	v_cvt_pk_bf16_f32 v56, v64, v65
	v_cvt_pk_bf16_f32 v57, v66, v67
	v_cvt_pk_bf16_f32 v58, v60, v61
	v_cvt_pk_bf16_f32 v59, v62, v63
	global_store_dwordx4 v174, v[56:59], s[92:93]
	v_fmamk_f32 v169, v251, 0x3a800000, v213
	v_rsq_f32_e32 v170, v169
	v_add_u32_e32 v174, 0x120000, v172
	v_mul_f32_e32 v168, 0xbfb8aa3b, v170
	v_mul_f32_e32 v160, v168, v48
	v_mul_f32_e32 v161, v168, v49
	v_mul_f32_e32 v162, v168, v50
	v_mul_f32_e32 v163, v168, v51
	v_mul_f32_e32 v164, v168, v44
	v_mul_f32_e32 v165, v168, v45
	v_mul_f32_e32 v166, v168, v46
	v_mul_f32_e32 v167, v168, v47
	v_exp_f32_e32 v160, v160
	v_exp_f32_e32 v161, v161
	v_exp_f32_e32 v162, v162
	v_exp_f32_e32 v163, v163
	v_exp_f32_e32 v164, v164
	v_exp_f32_e32 v165, v165
	v_exp_f32_e32 v166, v166
	v_exp_f32_e32 v167, v167
	v_fma_f32 v160, v160, v169, v169
	v_fma_f32 v161, v161, v169, v169
	v_fma_f32 v162, v162, v169, v169
	v_fma_f32 v163, v163, v169, v169
	v_fma_f32 v164, v164, v169, v169
	v_fma_f32 v165, v165, v169, v169
	v_fma_f32 v166, v166, v169, v169
	v_fma_f32 v167, v167, v169, v169
	v_rcp_f32_e32 v160, v160
	v_rcp_f32_e32 v161, v161
	v_rcp_f32_e32 v162, v162
	v_rcp_f32_e32 v163, v163
	v_rcp_f32_e32 v164, v164
	v_rcp_f32_e32 v165, v165
	v_rcp_f32_e32 v166, v166
	v_rcp_f32_e32 v167, v167
; __device__ __forceinline__ unsigned cvt_pk_bf16(float lo, float hi) { unsigned r; asm volatile("v_cvt_pk_bf16_f32 %0, %1, %2" : "=v"(r) : "v"(lo), "v"(hi)); return r; }
; __device__ __forceinline__ float rstd_of(float ss) { return __builtin_amdgcn_rsqf(ss * (1.0f / 1024.0f) + RMS_EPS_F); }
; __device__ __forceinline__ float silu_mul(float g, float u) { return g * __builtin_amdgcn_rcpf(1.0f + __builtin_amdgcn_exp2f(-1.4426950408889634f * g)) * u; }
; #define PG8_BAR __builtin_amdgcn_s_barrier()
;     __device__ __forceinline__ void operator()(const f32x4 (&acc)[2][2][4][2], const Unit& u, int wr, int wc, int fr_in, int fq_in) const {
;     ...
;             for (int m = 0; m < 4; ++m) { const int row = row0 + ai * HALF + m * 16; const float rs = rstd_of(ssq[ai][m]);
;                 const f32x4 g0 = acc[ai][0][m][0] * rs, g1 = acc[ai][0][m][1] * rs, u0 = acc[ai][1][m][0] * rs, u1 = acc[ai][1][m][1] * rs;
;                 u32x4 w; w.x = cvt_pk_bf16(silu_mul(g0[0], u0[0]), silu_mul(g0[1], u0[1])); w.y = cvt_pk_bf16(silu_mul(g0[2], u0[2]), silu_mul(g0[3], u0[3]));
;                 w.z = cvt_pk_bf16(silu_mul(g1[0], u1[0]), silu_mul(g1[1], u1[1])); w.w = cvt_pk_bf16(silu_mul(g1[2], u1[2]), silu_mul(g1[3], u1[3]));
;                 *(u32x4*)(act + (size_t)row * 4096 + col0) = w; }
; template <class Epi, class Sched, bool ALIGN_EPI = false, bool SP2 = false>
; __device__ __forceinline__ void gemm_phase(PG8_LAS unsigned char* lds, const Gemm g, const Sched& S, const Epi& E) {
;     ...
;         if constexpr (ALIGN_EPI) { if (wr == 0) PG8_BAR; }
;         if constexpr (!Epi::AFTER_DRAIN) { E(acc, cur, wr, wc, fr, fq); S.done(cur); }
;         if (!has_next) break;
	v_pk_mul_f32 v[48:49], v[48:49], v[40:41]
	v_pk_mul_f32 v[50:51], v[50:51], v[42:43]
	v_pk_mul_f32 v[44:45], v[44:45], v[36:37]
	v_pk_mul_f32 v[46:47], v[46:47], v[38:39]
	v_pk_mul_f32 v[48:49], v[48:49], v[160:161]
	v_pk_mul_f32 v[50:51], v[50:51], v[162:163]
	v_pk_mul_f32 v[44:45], v[44:45], v[164:165]
	v_pk_mul_f32 v[46:47], v[46:47], v[166:167]
	v_cvt_pk_bf16_f32 v40, v48, v49
	v_cvt_pk_bf16_f32 v41, v50, v51
	v_cvt_pk_bf16_f32 v42, v44, v45
	v_cvt_pk_bf16_f32 v43, v46, v47
	global_store_dwordx4 v174, v[40:43], s[92:93]
	v_fmamk_f32 v169, v252, 0x3a800000, v213
	v_rsq_f32_e32 v170, v169
	v_add_u32_e32 v174, 0x140000, v172
	v_mul_f32_e32 v168, 0xbfb8aa3b, v170
	v_mul_f32_e32 v160, v168, v32
	v_mul_f32_e32 v161, v168, v33
	v_mul_f32_e32 v162, v168, v34
	v_mul_f32_e32 v163, v168, v35
	v_mul_f32_e32 v164, v168, v28
	v_mul_f32_e32 v165, v168, v29
	v_mul_f32_e32 v166, v168, v30
	v_mul_f32_e32 v167, v168, v31
	v_exp_f32_e32 v160, v160
	v_exp_f32_e32 v161, v161
	v_exp_f32_e32 v162, v162
	v_exp_f32_e32 v163, v163
	v_exp_f32_e32 v164, v164
	v_exp_f32_e32 v165, v165
	v_exp_f32_e32 v166, v166
	v_exp_f32_e32 v167, v167
	v_fma_f32 v160, v160, v169, v169
	v_fma_f32 v161, v161, v169, v169
	v_fma_f32 v162, v162, v169, v169
	v_fma_f32 v163, v163, v169, v169
	v_fma_f32 v164, v164, v169, v169
	v_fma_f32 v165, v165, v169, v169
	v_fma_f32 v166, v166, v169, v169
	v_fma_f32 v167, v167, v169, v169
	v_rcp_f32_e32 v160, v160
	v_rcp_f32_e32 v161, v161
	v_rcp_f32_e32 v162, v162
	v_rcp_f32_e32 v163, v163
	v_rcp_f32_e32 v164, v164
	v_rcp_f32_e32 v165, v165
	v_rcp_f32_e32 v166, v166
	v_rcp_f32_e32 v167, v167
	v_pk_mul_f32 v[32:33], v[32:33], v[24:25]
	v_pk_mul_f32 v[34:35], v[34:35], v[26:27]
	v_pk_mul_f32 v[28:29], v[28:29], v[20:21]
	v_pk_mul_f32 v[30:31], v[30:31], v[22:23]
	v_pk_mul_f32 v[32:33], v[32:33], v[160:161]
	v_pk_mul_f32 v[34:35], v[34:35], v[162:163]
	v_pk_mul_f32 v[28:29], v[28:29], v[164:165]
	v_pk_mul_f32 v[30:31], v[30:31], v[166:167]
	v_cvt_pk_bf16_f32 v24, v32, v33
	v_cvt_pk_bf16_f32 v25, v34, v35
	v_cvt_pk_bf16_f32 v26, v28, v29
	v_cvt_pk_bf16_f32 v27, v30, v31
	global_store_dwordx4 v174, v[24:27], s[92:93]
	v_fmamk_f32 v169, v253, 0x3a800000, v213
	v_rsq_f32_e32 v170, v169
	v_add_u32_e32 v174, 0x160000, v172
	v_mul_f32_e32 v168, 0xbfb8aa3b, v170
	v_mul_f32_e32 v160, v168, v16
	v_mul_f32_e32 v161, v168, v17
	v_mul_f32_e32 v162, v168, v18
	v_mul_f32_e32 v163, v168, v19
	v_mul_f32_e32 v164, v168, v12
	v_mul_f32_e32 v165, v168, v13
	v_mul_f32_e32 v166, v168, v14
	v_mul_f32_e32 v167, v168, v15
	v_exp_f32_e32 v160, v160
	v_exp_f32_e32 v161, v161
	v_exp_f32_e32 v162, v162
	v_exp_f32_e32 v163, v163
	v_exp_f32_e32 v164, v164
	v_exp_f32_e32 v165, v165
	v_exp_f32_e32 v166, v166
	v_exp_f32_e32 v167, v167
	v_fma_f32 v160, v160, v169, v169
	v_fma_f32 v161, v161, v169, v169
	v_fma_f32 v162, v162, v169, v169
	v_fma_f32 v163, v163, v169, v169
	v_fma_f32 v164, v164, v169, v169
	v_fma_f32 v165, v165, v169, v169
	v_fma_f32 v166, v166, v169, v169
	v_fma_f32 v167, v167, v169, v169
	v_rcp_f32_e32 v160, v160
	v_rcp_f32_e32 v161, v161
	v_rcp_f32_e32 v162, v162
	v_rcp_f32_e32 v163, v163
	v_rcp_f32_e32 v164, v164
	v_rcp_f32_e32 v165, v165
	v_rcp_f32_e32 v166, v166
	v_rcp_f32_e32 v167, v167
	v_pk_mul_f32 v[16:17], v[16:17], v[8:9]
	v_pk_mul_f32 v[18:19], v[18:19], v[10:11]
	v_pk_mul_f32 v[12:13], v[12:13], v[4:5]
	v_pk_mul_f32 v[14:15], v[14:15], v[6:7]
	v_pk_mul_f32 v[16:17], v[16:17], v[160:161]
	v_pk_mul_f32 v[18:19], v[18:19], v[162:163]
	v_pk_mul_f32 v[12:13], v[12:13], v[164:165]
	v_pk_mul_f32 v[14:15], v[14:15], v[166:167]
	v_cvt_pk_bf16_f32 v8, v16, v17
	v_cvt_pk_bf16_f32 v9, v18, v19
	v_cvt_pk_bf16_f32 v10, v12, v13
	v_cvt_pk_bf16_f32 v11, v14, v15
	global_store_dwordx4 v174, v[8:11], s[92:93]
	s_andn2_b64 vcc, exec, s[40:41]
	s_cbranch_vccnz .LBB0_634
	s_andn2_b64 vcc, exec, s[6:7]
	s_cbranch_vccnz .LBB0_633
	s_barrier
	s_branch .LBB0_633
